# v31 + grid barrier: the first workgroup of each XCD to arrive issues an early buffer_wbl2 (write-back hint); the last arriver still performs the releasing write-back
# speedup vs baseline: 1.0193x; 1.0014x over previous
; __device__ __forceinline__ unsigned xb_ld(unsigned* p)              { return __hip_atomic_load(p, __ATOMIC_RELAXED, __HIP_MEMORY_SCOPE_AGENT); }
; __device__ __forceinline__ unsigned xb_add(unsigned* p, unsigned v) { return __hip_atomic_fetch_add(p, v, __ATOMIC_RELAXED, __HIP_MEMORY_SCOPE_AGENT); }
; #define XB_SPIN(cond, bar) do { unsigned _sp = 0; while (cond) { __builtin_amdgcn_s_sleep(1); \
;     if ((++_sp & 255u) == 0u) { if (xb_ld(&(bar)[XB_TMO])) break; if (_sp > XB_SPIN_CAP) { atomicAdd(&(bar)[XB_TMO], 1u); break; } } } } while (0)
; __device__ __forceinline__ void xcd_barrier(const XcdBarrier& b, const bool t0) {
;     ...
;         const unsigned old = xb_add(&bar[XB_XSUB(b.x)], 1u);
;         const unsigned gen = old / nloc;
;         if (old + 1u == (gen + 1u) * nloc) {
;             __builtin_amdgcn_fence(__ATOMIC_RELEASE, "agent");
;             asm volatile("s_waitcnt vmcnt(0)" ::: "memory");
;             const unsigned og = xb_add(&bar[XB_TOP], 1u);
;             const unsigned tg = og / nx;
;             if (og + 1u == (tg + 1u) * nx) xb_add(&bar[XB_TOPGEN], 1u);
;             else XB_SPIN(xb_ld(&bar[XB_TOPGEN]) == tg, bar);
;             __builtin_amdgcn_fence(__ATOMIC_ACQUIRE, "agent");
;             xb_add(&bar[XB_XGEN(b.x)], 1u);
;             asm volatile("s_waitcnt vmcnt(0)" ::: "memory");
;         } else {
;             XB_SPIN(xb_ld(&bar[XB_XGEN(b.x)]) == gen, bar);
.LBB0_178:
	s_or_b64 exec, exec, s[10:11]
	v_cvt_f32_u32_e32 v4, v2
	s_waitcnt vmcnt(0)
	v_readfirstlane_b32 s0, v3
	v_sub_u32_e32 v3, 0, v2
	v_rcp_iflag_f32_e32 v4, v4
	v_add_u32_e32 v5, s0, v1
	v_mul_f32_e32 v4, 0x4f7ffffe, v4
	v_cvt_u32_f32_e32 v4, v4
	v_mul_lo_u32 v1, v3, v4
	v_mul_hi_u32 v1, v4, v1
	v_add_u32_e32 v1, v4, v1
	v_mul_hi_u32 v1, v5, v1
	v_mul_lo_u32 v3, v1, v2
	v_sub_u32_e32 v3, v5, v3
	v_add_u32_e32 v4, 1, v1
	v_cmp_ge_u32_e32 vcc, v3, v2
	s_nop 1
	v_cndmask_b32_e32 v1, v1, v4, vcc
	v_sub_u32_e32 v4, v3, v2
	v_cndmask_b32_e32 v3, v3, v4, vcc
	v_add_u32_e32 v4, 1, v1
	v_cmp_ge_u32_e32 vcc, v3, v2
	v_add_u32_e32 v3, 1, v5
	s_nop 0
	v_cndmask_b32_e32 v1, v1, v4, vcc
	v_mul_lo_u32 v4, v2, v1
	v_add_u32_e32 v2, v4, v2
	v_cmp_ne_u32_e32 vcc, v3, v2
	s_and_saveexec_b64 s[0:1], vcc
	s_xor_b64 s[8:9], exec, s[0:1]
	s_cbranch_execz .LBB0_192
	v_cmp_eq_u32_e32 vcc, v5, v4
	s_cbranch_vccz .Lbar_early_0
	buffer_wbl2 sc1
.Lbar_early_0:
	s_waitcnt lgkmcnt(0)
	v_mov_b32_e32 v0, 0x2000
	global_load_dword v0, v0, s[6:7] offset:1024 sc1
	s_add_u32 s16, s6, 0x2400
	s_addc_u32 s17, s7, 0
	s_waitcnt vmcnt(0)
	v_cmp_eq_u32_e32 vcc, v0, v1
	s_and_saveexec_b64 s[10:11], vcc
	s_cbranch_execz .LBB0_191
	s_add_u32 s12, s78, 0x4200
	s_addc_u32 s13, s79, 0
	s_mov_b32 s0, 1
	s_mov_b64 s[18:19], 0
	v_mov_b32_e32 v0, 0
	s_branch .LBB0_182

; __device__ __forceinline__ unsigned xb_ld(unsigned* p)              { return __hip_atomic_load(p, __ATOMIC_RELAXED, __HIP_MEMORY_SCOPE_AGENT); }
; __device__ __forceinline__ unsigned xb_add(unsigned* p, unsigned v) { return __hip_atomic_fetch_add(p, v, __ATOMIC_RELAXED, __HIP_MEMORY_SCOPE_AGENT); }
; #define XB_SPIN(cond, bar) do { unsigned _sp = 0; while (cond) { __builtin_amdgcn_s_sleep(1); \
;     if ((++_sp & 255u) == 0u) { if (xb_ld(&(bar)[XB_TMO])) break; if (_sp > XB_SPIN_CAP) { atomicAdd(&(bar)[XB_TMO], 1u); break; } } } } while (0)
; __device__ __forceinline__ void xcd_barrier(const XcdBarrier& b, const bool t0) {
;     ...
;         const unsigned old = xb_add(&bar[XB_XSUB(b.x)], 1u);
;         const unsigned gen = old / nloc;
;         if (old + 1u == (gen + 1u) * nloc) {
;             __builtin_amdgcn_fence(__ATOMIC_RELEASE, "agent");
;             asm volatile("s_waitcnt vmcnt(0)" ::: "memory");
;             const unsigned og = xb_add(&bar[XB_TOP], 1u);
;             const unsigned tg = og / nx;
;             if (og + 1u == (tg + 1u) * nx) xb_add(&bar[XB_TOPGEN], 1u);
;             else XB_SPIN(xb_ld(&bar[XB_TOPGEN]) == tg, bar);
;             __builtin_amdgcn_fence(__ATOMIC_ACQUIRE, "agent");
;             xb_add(&bar[XB_XGEN(b.x)], 1u);
;             asm volatile("s_waitcnt vmcnt(0)" ::: "memory");
;         } else {
;             XB_SPIN(xb_ld(&bar[XB_XGEN(b.x)]) == gen, bar);
.LBB0_865:
	s_or_b64 exec, exec, s[8:9]
	v_cvt_f32_u32_e32 v4, v2
	s_waitcnt vmcnt(0)
	v_readfirstlane_b32 s0, v3
	v_sub_u32_e32 v3, 0, v2
	v_rcp_iflag_f32_e32 v4, v4
	v_add_u32_e32 v5, s0, v1
	v_mul_f32_e32 v4, 0x4f7ffffe, v4
	v_cvt_u32_f32_e32 v4, v4
	v_mul_lo_u32 v1, v3, v4
	v_mul_hi_u32 v1, v4, v1
	v_add_u32_e32 v1, v4, v1
	v_mul_hi_u32 v1, v5, v1
	v_mul_lo_u32 v3, v1, v2
	v_sub_u32_e32 v3, v5, v3
	v_add_u32_e32 v4, 1, v1
	v_cmp_ge_u32_e32 vcc, v3, v2
	s_nop 1
	v_cndmask_b32_e32 v1, v1, v4, vcc
	v_sub_u32_e32 v4, v3, v2
	v_cndmask_b32_e32 v3, v3, v4, vcc
	v_add_u32_e32 v4, 1, v1
	v_cmp_ge_u32_e32 vcc, v3, v2
	v_add_u32_e32 v3, 1, v5
	s_nop 0
	v_cndmask_b32_e32 v1, v1, v4, vcc
	v_mul_lo_u32 v4, v2, v1
	v_add_u32_e32 v2, v4, v2
	v_cmp_ne_u32_e32 vcc, v3, v2
	s_and_saveexec_b64 s[0:1], vcc
	s_xor_b64 s[6:7], exec, s[0:1]
	s_cbranch_execz .LBB0_879
	v_cmp_eq_u32_e32 vcc, v5, v4
	s_cbranch_vccz .Lbar_early_7
	buffer_wbl2 sc1
.Lbar_early_7:
	s_waitcnt lgkmcnt(0)
	v_mov_b32_e32 v0, 0x2000
	global_load_dword v0, v0, s[4:5] offset:1024 sc1
	s_add_u32 s12, s4, 0x2400
	s_addc_u32 s13, s5, 0
	s_waitcnt vmcnt(0)
	v_cmp_eq_u32_e32 vcc, v0, v1
	s_and_saveexec_b64 s[8:9], vcc
	s_cbranch_execz .LBB0_878
	s_add_u32 s10, s78, 0x4200
	s_addc_u32 s11, s79, 0
	s_mov_b32 s0, 1
	s_mov_b64 s[16:17], 0
	v_mov_b32_e32 v0, 0
	s_branch .LBB0_869

; __device__ __forceinline__ unsigned xb_ld(unsigned* p)              { return __hip_atomic_load(p, __ATOMIC_RELAXED, __HIP_MEMORY_SCOPE_AGENT); }
; __device__ __forceinline__ unsigned xb_add(unsigned* p, unsigned v) { return __hip_atomic_fetch_add(p, v, __ATOMIC_RELAXED, __HIP_MEMORY_SCOPE_AGENT); }
; #define XB_SPIN(cond, bar) do { unsigned _sp = 0; while (cond) { __builtin_amdgcn_s_sleep(1); \
;     if ((++_sp & 255u) == 0u) { if (xb_ld(&(bar)[XB_TMO])) break; if (_sp > XB_SPIN_CAP) { atomicAdd(&(bar)[XB_TMO], 1u); break; } } } } while (0)
; __device__ __forceinline__ void xcd_barrier(const XcdBarrier& b, const bool t0) {
;     ...
;         const unsigned old = xb_add(&bar[XB_XSUB(b.x)], 1u);
;         const unsigned gen = old / nloc;
;         if (old + 1u == (gen + 1u) * nloc) {
;             __builtin_amdgcn_fence(__ATOMIC_RELEASE, "agent");
;             asm volatile("s_waitcnt vmcnt(0)" ::: "memory");
;             const unsigned og = xb_add(&bar[XB_TOP], 1u);
;             const unsigned tg = og / nx;
;             if (og + 1u == (tg + 1u) * nx) xb_add(&bar[XB_TOPGEN], 1u);
;             else XB_SPIN(xb_ld(&bar[XB_TOPGEN]) == tg, bar);
;             __builtin_amdgcn_fence(__ATOMIC_ACQUIRE, "agent");
;             xb_add(&bar[XB_XGEN(b.x)], 1u);
;             asm volatile("s_waitcnt vmcnt(0)" ::: "memory");
;         } else {
;             XB_SPIN(xb_ld(&bar[XB_XGEN(b.x)]) == gen, bar);
.LBB0_1577:
	s_or_b64 exec, exec, s[8:9]
	v_cvt_f32_u32_e32 v4, v2
	s_waitcnt vmcnt(0)
	v_readfirstlane_b32 s6, v3
	v_sub_u32_e32 v3, 0, v2
	v_rcp_iflag_f32_e32 v4, v4
	v_add_u32_e32 v5, s6, v1
	v_mul_f32_e32 v4, 0x4f7ffffe, v4
	v_cvt_u32_f32_e32 v4, v4
	v_mul_lo_u32 v1, v3, v4
	v_mul_hi_u32 v1, v4, v1
	v_add_u32_e32 v1, v4, v1
	v_mul_hi_u32 v1, v5, v1
	v_mul_lo_u32 v3, v1, v2
	v_sub_u32_e32 v3, v5, v3
	v_add_u32_e32 v4, 1, v1
	v_cmp_ge_u32_e32 vcc, v3, v2
	s_nop 1
	v_cndmask_b32_e32 v1, v1, v4, vcc
	v_sub_u32_e32 v4, v3, v2
	v_cndmask_b32_e32 v3, v3, v4, vcc
	v_add_u32_e32 v4, 1, v1
	v_cmp_ge_u32_e32 vcc, v3, v2
	v_add_u32_e32 v3, 1, v5
	s_nop 0
	v_cndmask_b32_e32 v1, v1, v4, vcc
	v_mul_lo_u32 v4, v2, v1
	v_add_u32_e32 v2, v4, v2
	v_cmp_ne_u32_e32 vcc, v3, v2
	s_and_saveexec_b64 s[6:7], vcc
	s_xor_b64 s[6:7], exec, s[6:7]
	s_cbranch_execz .LBB0_1591
	v_cmp_eq_u32_e32 vcc, v5, v4
	s_cbranch_vccz .Lbar_early_15
	buffer_wbl2 sc1
.Lbar_early_15:
	s_waitcnt lgkmcnt(0)
	v_mov_b32_e32 v0, 0x2000
	global_load_dword v0, v0, s[4:5] offset:1024 sc1
	s_add_u32 s12, s4, 0x2400
	s_addc_u32 s13, s5, 0
	s_waitcnt vmcnt(0)
	v_cmp_eq_u32_e32 vcc, v0, v1
	s_and_saveexec_b64 s[8:9], vcc
	s_cbranch_execz .LBB0_1590
	s_add_u32 s10, s78, 0x4200
	s_addc_u32 s11, s79, 0
	s_mov_b32 s24, 1
	s_mov_b64 s[14:15], 0
	v_mov_b32_e32 v0, 0
	s_branch .LBB0_1581
